# pass2: V chunk loads hoisted into the second direction iteration, gain vectors reused across the four gating blocks instead of reloading behind each store (on top of the peeled GEMM first iteration)
# speedup vs baseline: 1.0142x; 1.0030x over previous
; #define LAS __attribute__((address_space(3)))
; __device__ __forceinline__ unsigned pk2(float lo, float hi) { const f32x2_t v = {lo, hi}; return __builtin_bit_cast(unsigned, __builtin_convertvector(v, bf16x2_t)); }
; __device__ __forceinline__ f32x4 mfma16(bf16x8 a, bf16x8 b, f32x4 c) { return __builtin_amdgcn_mfma_f32_16x16x32_bf16(a, b, c, 0, 0, 0); }
; __device__ __forceinline__ void hgrn_pass2(const bf16* PROJ, const bf16* ST, const float* lbl, const float* gain, int e, bf16* MIX, int L, LAS unsigned char* lds) {
;     ...
;         { v4u cv[4]; hgrn_ld_chunks(pb + 1536, tid, cv); hgrn_st_chunks(SI, tid, cv); }
;         __syncthreads();
;         hgrn_build_vt(SI, VT, i, tq);
;         v4u gch[4];
; #pragma unroll
;         for (int m = 0; m < 4; ++m) { const int cc = lane + 64 * m; gch[m] = *(const v4u*)(pb + (size_t)(16 * I + (cc >> 4)) * EIN + 2048 + 8 * (cc & 15)); }
;         __syncthreads();
; #pragma unroll
;         for (int kp = 0; kp < 4; ++kp) {
;             v4u aw; aw.x = pk2(X[2 * kp][0], X[2 * kp][1]); aw.y = pk2(X[2 * kp][2], X[2 * kp][3]); aw.z = pk2(X[2 * kp + 1][0], X[2 * kp + 1][1]); aw.w = pk2(X[2 * kp + 1][2], X[2 * kp + 1][3]);
;             const bf16x8 af = as_bf8(aw);
; #pragma unroll
;             for (int dt = 0; dt < 8; ++dt) { const LAS unsigned char* vr = VT + (16 * dt + r16) * LSTR;
;                 const v2u lo = *(const LAS v2u*)(vr + (32 * kp + 4 * g4) * 2), hi = *(const LAS v2u*)(vr + (32 * kp + 16 + 4 * g4) * 2);
;                 v4u bw; bw.x = lo.x; bw.y = lo.y; bw.z = hi.x; bw.w = hi.y;
;                 O[dt] = mfma16(af, as_bf8(bw), O[dt]); }
;         }
.LBB0_270:
	s_waitcnt vmcnt(3)
	ds_write_b128 v162, v[232:235]
	s_waitcnt vmcnt(2)
	ds_write_b128 v163, v[236:239]
	s_waitcnt vmcnt(1)
	ds_write_b128 v164, v[240:243]
	s_waitcnt vmcnt(0)
	ds_write_b128 v165, v[252:255]
	s_waitcnt lgkmcnt(0)
	s_barrier
	ds_read_u16 v66, v152
	ds_read_u16 v67, v152 offset:272
	ds_read_u16 v68, v152 offset:544
	ds_read_u16 v69, v152 offset:816
	ds_read_u16 v70, v152 offset:1088
	ds_read_u16 v71, v152 offset:1360
	ds_read_u16 v72, v152 offset:1632
	ds_read_u16 v73, v152 offset:1904
	ds_read_u16 v74, v152 offset:2176
	ds_read_u16 v75, v152 offset:2448
	ds_read_u16 v76, v152 offset:2720
	ds_read_u16 v77, v152 offset:2992
	ds_read_u16 v78, v152 offset:3264
	ds_read_u16 v79, v152 offset:3536
	ds_read_u16 v80, v152 offset:3808
	ds_read_u16 v81, v152 offset:4080
	ds_read_u16 v82, v152 offset:4352
	ds_read_u16 v83, v152 offset:4624
	ds_read_u16 v84, v152 offset:4896
	ds_read_u16 v85, v152 offset:5168
	ds_read_u16 v122, v152 offset:5440
	ds_read_u16 v123, v152 offset:5712
	ds_read_u16 v124, v152 offset:5984
	ds_read_u16 v125, v152 offset:6256
	ds_read_u16 v126, v152 offset:6528
	ds_read_u16 v127, v152 offset:6800
	ds_read_u16 v128, v152 offset:7072
	ds_read_u16 v129, v152 offset:7344
	ds_read_u16 v130, v152 offset:7616
	ds_read_u16 v131, v152 offset:7888
	ds_read_u16 v162, v152 offset:8160
	ds_read_u16 v163, v152 offset:8432
	s_waitcnt lgkmcnt(14)
	v_lshl_or_b32 v66, v67, 16, v66
	v_lshl_or_b32 v67, v69, 16, v68
	v_lshl_or_b32 v68, v71, 16, v70
	v_lshl_or_b32 v69, v73, 16, v72
	ds_write_b128 v153, v[66:69]
	v_lshl_or_b32 v66, v75, 16, v74
	v_lshl_or_b32 v67, v77, 16, v76
	v_lshl_or_b32 v68, v79, 16, v78
	v_lshl_or_b32 v69, v81, 16, v80
	ds_write_b128 v153, v[66:69] offset:16
	v_lshl_or_b32 v66, v83, 16, v82
	s_waitcnt lgkmcnt(14)
	v_lshl_or_b32 v67, v85, 16, v84
	s_waitcnt lgkmcnt(12)
	v_lshl_or_b32 v68, v123, 16, v122
	s_waitcnt lgkmcnt(10)
	v_lshl_or_b32 v69, v125, 16, v124
	ds_write_b128 v153, v[66:69] offset:32
	s_waitcnt lgkmcnt(9)
	v_lshl_or_b32 v66, v127, 16, v126
	s_waitcnt lgkmcnt(7)
	v_lshl_or_b32 v67, v129, 16, v128
	s_waitcnt lgkmcnt(5)
	v_lshl_or_b32 v68, v131, 16, v130
	s_waitcnt lgkmcnt(3)
	v_lshl_or_b32 v69, v163, 16, v162
	ds_write_b128 v153, v[66:69] offset:48
	v_lshl_add_u64 v[66:67], s[36:37], 0, v[108:109]
	v_lshl_add_u64 v[66:67], v[66:67], 0, v[64:65]
	v_add_co_u32_e32 v66, vcc, s93, v66
	v_lshl_add_u64 v[68:69], s[36:37], 0, v[112:113]
	s_nop 0
	v_addc_co_u32_e32 v67, vcc, 0, v67, vcc
	v_lshl_add_u64 v[68:69], v[68:69], 0, v[64:65]
	v_add_co_u32_e32 v68, vcc, s93, v68
	v_cvt_pk_bf16_f32 v48, v48, v49
	s_nop 0
	v_addc_co_u32_e32 v69, vcc, 0, v69, vcc
	global_load_dwordx4 v[78:81], v[66:67], off
	global_load_dwordx4 v[74:77], v[68:69], off
	v_lshl_add_u64 v[66:67], s[36:37], 0, v[116:117]
	v_lshl_add_u64 v[66:67], v[66:67], 0, v[64:65]
	v_add_co_u32_e32 v66, vcc, s93, v66
	v_lshl_add_u64 v[68:69], s[36:37], 0, v[120:121]
	s_nop 0
	v_addc_co_u32_e32 v67, vcc, 0, v67, vcc
	v_lshl_add_u64 v[68:69], v[68:69], 0, v[64:65]
	v_add_co_u32_e32 v68, vcc, s93, v68
	v_cvt_pk_bf16_f32 v49, v50, v51
	s_nop 0
	v_addc_co_u32_e32 v69, vcc, 0, v69, vcc
	global_load_dwordx4 v[70:73], v[66:67], off
	s_nop 0
	global_load_dwordx4 v[66:69], v[68:69], off
	s_waitcnt lgkmcnt(0)
	s_barrier
	v_cvt_pk_bf16_f32 v50, v44, v45
	v_cvt_pk_bf16_f32 v51, v46, v47
	ds_read2_b64 v[44:47], v147 offset1:4
	v_add_u32_e32 v82, 0x1000, v147
	s_waitcnt lgkmcnt(0)
	v_mfma_f32_16x16x32_bf16 v[44:47], v[48:51], v[44:47], v[60:63]
	s_nop 2
	ds_read2_b64 v[60:63], v82 offset0:32 offset1:36
	v_add_u32_e32 v83, 0x2000, v147
	v_add_u32_e32 v84, 0x3000, v147
	s_waitcnt lgkmcnt(0)
	v_mfma_f32_16x16x32_bf16 v[56:59], v[48:51], v[60:63], v[56:59]
	ds_read2_b64 v[60:63], v83 offset0:64 offset1:68
	v_add_u32_e32 v85, 0x4000, v147
	v_add_u32_e32 v122, 0x5000, v147
	s_waitcnt lgkmcnt(0)
	v_mfma_f32_16x16x32_bf16 v[52:55], v[48:51], v[60:63], v[52:55]
	ds_read2_b64 v[60:63], v84 offset0:96 offset1:100
	v_add_u32_e32 v123, 0x6000, v147
	v_add_u32_e32 v124, 0x7000, v147
	s_waitcnt lgkmcnt(0)
	v_mfma_f32_16x16x32_bf16 v[40:43], v[48:51], v[60:63], v[40:43]
	ds_read2_b64 v[60:63], v85 offset0:128 offset1:132
	v_cvt_pk_bf16_f32 v20, v20, v21
	v_cvt_pk_bf16_f32 v21, v22, v23
	s_waitcnt lgkmcnt(0)
	v_mfma_f32_16x16x32_bf16 v[36:39], v[48:51], v[60:63], v[36:39]
	ds_read2_b64 v[60:63], v122 offset0:160 offset1:164
	v_cvt_pk_bf16_f32 v22, v16, v17
	v_cvt_pk_bf16_f32 v23, v18, v19
	s_waitcnt lgkmcnt(0)
	v_mfma_f32_16x16x32_bf16 v[32:35], v[48:51], v[60:63], v[32:35]
	ds_read2_b64 v[60:63], v123 offset0:192 offset1:196
	ds_read2_b64 v[16:19], v147 offset0:8 offset1:12
	v_cvt_pk_bf16_f32 v12, v12, v13
	s_waitcnt lgkmcnt(1)
	v_mfma_f32_16x16x32_bf16 v[28:31], v[48:51], v[60:63], v[28:31]
	ds_read2_b64 v[60:63], v124 offset0:224 offset1:228
	v_cvt_pk_bf16_f32 v13, v14, v15
	v_cvt_pk_bf16_f32 v14, v8, v9
	s_waitcnt lgkmcnt(0)
	v_mfma_f32_16x16x32_bf16 v[24:27], v[48:51], v[60:63], v[24:27]
	ds_read2_b64 v[48:51], v83 offset0:72 offset1:76
	v_cvt_pk_bf16_f32 v15, v10, v11
	ds_read2_b64 v[8:11], v147 offset0:16 offset1:20
	s_waitcnt lgkmcnt(1)
	v_mfma_f32_16x16x32_bf16 v[48:51], v[20:23], v[48:51], v[52:55]
	s_mov_b32 s2, 0x358637bd
	s_nop 1
	ds_read2_b64 v[52:55], v84 offset0:104 offset1:108
	s_brev_b32 s20, 60
	s_waitcnt lgkmcnt(0)
	v_mfma_f32_16x16x32_bf16 v[40:43], v[20:23], v[52:55], v[40:43]
	ds_read2_b64 v[52:55], v85 offset0:136 offset1:140
	s_lshl_b32 s90, s96, 2
	s_mov_b32 s86, 0x800000
	v_mfma_f32_16x16x32_bf16 v[16:19], v[20:23], v[16:19], v[44:47]
	s_nop 2
	ds_read2_b64 v[44:47], v82 offset0:40 offset1:44
	s_waitcnt lgkmcnt(1)
; #define LAS __attribute__((address_space(3)))
; __device__ __forceinline__ unsigned pk2(float lo, float hi) { const f32x2_t v = {lo, hi}; return __builtin_bit_cast(unsigned, __builtin_convertvector(v, bf16x2_t)); }
; __device__ __forceinline__ f32x4 mfma16(bf16x8 a, bf16x8 b, f32x4 c) { return __builtin_amdgcn_mfma_f32_16x16x32_bf16(a, b, c, 0, 0, 0); }
; __device__ __forceinline__ void hgrn_pass2(const bf16* PROJ, const bf16* ST, const float* lbl, const float* gain, int e, bf16* MIX, int L, LAS unsigned char* lds) {
;     ...
; #pragma unroll
;         for (int kp = 0; kp < 4; ++kp) {
;             v4u aw; aw.x = pk2(X[2 * kp][0], X[2 * kp][1]); aw.y = pk2(X[2 * kp][2], X[2 * kp][3]); aw.z = pk2(X[2 * kp + 1][0], X[2 * kp + 1][1]); aw.w = pk2(X[2 * kp + 1][2], X[2 * kp + 1][3]);
;             const bf16x8 af = as_bf8(aw);
; #pragma unroll
;             for (int dt = 0; dt < 8; ++dt) { const LAS unsigned char* vr = VT + (16 * dt + r16) * LSTR;
;                 const v2u lo = *(const LAS v2u*)(vr + (32 * kp + 4 * g4) * 2), hi = *(const LAS v2u*)(vr + (32 * kp + 16 + 4 * g4) * 2);
;                 v4u bw; bw.x = lo.x; bw.y = lo.y; bw.z = hi.x; bw.w = hi.y;
;                 O[dt] = mfma16(af, as_bf8(bw), O[dt]); }
;         }
; #pragma unroll
;         for (int r = 0; r < 4; ++r) { float ss = 0.f;
; #pragma unroll
;             for (int dt = 0; dt < 8; ++dt) ss += O[dt][r] * O[dt][r];
;             ss += __shfl_xor(ss, 1); ss += __shfl_xor(ss, 2); ss += __shfl_xor(ss, 4); ss += __shfl_xor(ss, 8);
	v_mfma_f32_16x16x32_bf16 v[36:39], v[20:23], v[52:55], v[36:39]
	ds_read2_b64 v[52:55], v122 offset0:168 offset1:172
	v_mfma_f32_16x16x32_bf16 v[8:11], v[12:15], v[8:11], v[16:19]
	s_nop 2
	ds_read2_b64 v[16:19], v82 offset0:48 offset1:52
	s_waitcnt lgkmcnt(2)
	v_mfma_f32_16x16x32_bf16 v[44:47], v[20:23], v[44:47], v[56:59]
	s_waitcnt lgkmcnt(1)
	v_mfma_f32_16x16x32_bf16 v[32:35], v[20:23], v[52:55], v[32:35]
	ds_read2_b64 v[52:55], v123 offset0:200 offset1:204
	s_waitcnt lgkmcnt(1)
	v_mfma_f32_16x16x32_bf16 v[16:19], v[12:15], v[16:19], v[44:47]
	s_nop 2
	ds_read2_b64 v[44:47], v84 offset0:112 offset1:116
	s_waitcnt lgkmcnt(1)
	v_mfma_f32_16x16x32_bf16 v[28:31], v[20:23], v[52:55], v[28:31]
	ds_read2_b64 v[52:55], v124 offset0:232 offset1:236
	s_waitcnt lgkmcnt(1)
	v_mfma_f32_16x16x32_bf16 v[40:43], v[12:15], v[44:47], v[40:43]
	ds_read2_b64 v[44:47], v85 offset0:144 offset1:148
	s_waitcnt lgkmcnt(1)
	v_mfma_f32_16x16x32_bf16 v[20:23], v[20:23], v[52:55], v[24:27]
	s_nop 2
	ds_read2_b64 v[24:27], v83 offset0:80 offset1:84
	s_waitcnt lgkmcnt(1)
	v_mfma_f32_16x16x32_bf16 v[36:39], v[12:15], v[44:47], v[36:39]
	ds_read2_b64 v[44:47], v122 offset0:176 offset1:180
	s_waitcnt lgkmcnt(1)
	v_mfma_f32_16x16x32_bf16 v[24:27], v[12:15], v[24:27], v[48:51]
	s_nop 2
	v_cvt_pk_bf16_f32 v48, v4, v5
	v_cvt_pk_bf16_f32 v49, v6, v7
	v_cvt_pk_bf16_f32 v50, v0, v1
	v_cvt_pk_bf16_f32 v51, v2, v3
	ds_read2_b64 v[0:3], v147 offset0:24 offset1:28
	s_waitcnt lgkmcnt(1)
	v_mfma_f32_16x16x32_bf16 v[32:35], v[12:15], v[44:47], v[32:35]
	ds_read2_b64 v[44:47], v123 offset0:208 offset1:212
	ds_read2_b64 v[4:7], v82 offset0:56 offset1:60
	s_waitcnt lgkmcnt(2)
	v_mfma_f32_16x16x32_bf16 v[0:3], v[48:51], v[0:3], v[8:11]
	s_nop 2
	ds_read2_b64 v[8:11], v83 offset0:88 offset1:92
	s_waitcnt lgkmcnt(2)
	v_mfma_f32_16x16x32_bf16 v[28:31], v[12:15], v[44:47], v[28:31]
	ds_read2_b64 v[44:47], v124 offset0:240 offset1:244
	s_waitcnt lgkmcnt(1)
	v_mfma_f32_16x16x32_bf16 v[8:11], v[48:51], v[8:11], v[24:27]
	s_nop 2
	ds_read2_b64 v[24:27], v123 offset0:216 offset1:220
	s_waitcnt lgkmcnt(1)
	v_mfma_f32_16x16x32_bf16 v[44:47], v[12:15], v[44:47], v[20:23]
	ds_read2_b64 v[12:15], v84 offset0:120 offset1:124
	v_mfma_f32_16x16x32_bf16 v[4:7], v[48:51], v[4:7], v[16:19]
	s_nop 0
	ds_read2_b64 v[20:23], v122 offset0:184 offset1:188
	s_nop 0
	ds_read2_b64 v[16:19], v85 offset0:152 offset1:156
	s_waitcnt lgkmcnt(3)
	v_mfma_f32_16x16x32_bf16 v[24:27], v[48:51], v[24:27], v[28:31]
	s_nop 2
	ds_read2_b64 v[28:31], v124 offset0:248 offset1:252
	s_waitcnt lgkmcnt(3)
	v_mfma_f32_16x16x32_bf16 v[12:15], v[48:51], v[12:15], v[40:43]
	s_waitcnt lgkmcnt(1)
	v_mfma_f32_16x16x32_bf16 v[16:19], v[48:51], v[16:19], v[36:39]
	s_nop 0
	v_mul_f32_e64 v40, v4, v4
	v_mul_f32_e64 v41, v5, v5
	v_pk_fma_f32 v[40:41], v[0:1], v[0:1], v[40:41]
	v_mfma_f32_16x16x32_bf16 v[20:23], v[48:51], v[20:23], v[32:35]
	v_mov_b32_e32 v38, v9
	v_mov_b32_e32 v39, v13
	v_pk_mul_f32 v[38:39], v[38:39], v[38:39]
	s_waitcnt lgkmcnt(0)
	v_mfma_f32_16x16x32_bf16 v[28:31], v[48:51], v[28:31], v[44:47]
	v_mov_b32_e32 v32, v8
	v_mov_b32_e32 v33, v12
	v_pk_mul_f32 v[32:33], v[32:33], v[32:33]
	v_mov_b32_e32 v34, v16
	v_mov_b32_e32 v35, v20
	v_mov_b32_e32 v42, v17
	v_mov_b32_e32 v43, v21
	v_mov_b32_e32 v46, v38
	v_mov_b32_e32 v47, v32
	v_pk_mul_f32 v[34:35], v[34:35], v[34:35]
	v_pk_mul_f32 v[42:43], v[42:43], v[42:43]
	v_pk_add_f32 v[40:41], v[40:41], v[46:47] op_sel:[1,0] op_sel_hi:[0,1]
	v_mov_b32_e32 v32, v39
	v_mov_b32_e32 v36, v24
	v_mov_b32_e32 v37, v28
	v_mov_b32_e32 v44, v25
	v_mov_b32_e32 v45, v29
	v_pk_add_f32 v[32:33], v[40:41], v[32:33]
	v_mov_b32_e32 v38, v42
	v_mov_b32_e32 v39, v34
	v_pk_mul_f32 v[36:37], v[36:37], v[36:37]
	v_pk_mul_f32 v[44:45], v[44:45], v[44:45]
	v_pk_add_f32 v[32:33], v[32:33], v[38:39]
	v_mov_b32_e32 v34, v43
	v_pk_add_f32 v[32:33], v[32:33], v[34:35]
	v_mov_b32_e32 v34, v44
	v_mov_b32_e32 v35, v36
	v_pk_add_f32 v[32:33], v[32:33], v[34:35]
	v_mov_b32_e32 v36, v45
	v_pk_add_f32 v[32:33], v[32:33], v[36:37]
	ds_bpermute_b32 v35, v142, v33
	ds_bpermute_b32 v34, v142, v32
	v_mov_b64_e32 v[40:41], s[2:3]
	s_mov_b32 s2, 0x800000
	v_mov_b32_e32 v37, v15
	v_mov_b32_e32 v38, v19
	s_waitcnt lgkmcnt(0)
	v_pk_add_f32 v[32:33], v[32:33], v[34:35]
	ds_bpermute_b32 v35, v143, v33
	ds_bpermute_b32 v34, v143, v32
	v_mov_b32_e32 v39, v23
	v_pk_mul_f32 v[38:39], v[38:39], v[38:39]
	v_mov_b32_e32 v42, v27
	v_mov_b32_e32 v43, v31
	s_waitcnt lgkmcnt(0)
	v_pk_add_f32 v[32:33], v[32:33], v[34:35]
	ds_bpermute_b32 v35, v144, v33
	ds_bpermute_b32 v34, v144, v32
	v_pk_mul_f32 v[42:43], v[42:43], v[42:43]
	v_readlane_b32 s3, v246, 1
	s_waitcnt lgkmcnt(0)
	v_pk_add_f32 v[32:33], v[32:33], v[34:35]
	ds_bpermute_b32 v35, v145, v33
	ds_bpermute_b32 v34, v145, v32
	s_waitcnt lgkmcnt(0)
; #define LAS __attribute__((address_space(3)))
; __device__ __forceinline__ unsigned f2bf(float f) { return pk2(f, 0.f) & 0xffffu; }
; __device__ __forceinline__ void hgrn_pass2(const bf16* PROJ, const bf16* ST, const float* lbl, const float* gain, int e, bf16* MIX, int L, LAS unsigned char* lds) {
;     ...
; #pragma unroll
;         for (int r = 0; r < 4; ++r) { float ss = 0.f;
; #pragma unroll
;             for (int dt = 0; dt < 8; ++dt) ss += O[dt][r] * O[dt][r];
;             ss += __shfl_xor(ss, 1); ss += __shfl_xor(ss, 2); ss += __shfl_xor(ss, 4); ss += __shfl_xor(ss, 8);
;             const float rs = rsqrtf(ss * (1.0f / 128.0f) + 1e-6f);
; #pragma unroll
;             for (int dt = 0; dt < 8; ++dt) *(LAS unsigned short*)(BQ + (16 * I + 4 * g4 + r) * LSTR + (16 * dt + r16) * 2) = (unsigned short)f2bf(O[dt][r] * rs); }
; #pragma unroll
;         for (int m = 0; m < 4; ++m) { const int cc = lane + 64 * m, tl = cc >> 4, c8 = cc & 15;
;             const v4u ow = *(const LAS v4u*)(BQ + (16 * I + tl) * LSTR + c8 * 16);
;             const f32x4 ga = *(const f32x4*)(gain + 128 * h + 8 * c8), gb = *(const f32x4*)(gain + 128 * h + 8 * c8 + 4);
	v_pk_add_f32 v[32:33], v[32:33], v[34:35]
	s_nop 0
	v_pk_fma_f32 v[32:33], v[32:33], s[20:21], v[40:41] op_sel_hi:[1,0,0]
	s_nop 0
	v_mul_f32_e32 v34, 0x4b800000, v33
	v_cmp_gt_f32_e32 vcc, s2, v33
	s_nop 1
	v_cndmask_b32_e32 v33, v33, v34, vcc
	v_rsq_f32_e32 v33, v33
	v_pk_mul_f32 v[34:35], v[6:7], v[6:7]
	v_mul_f32_e32 v36, 0x45800000, v33
	v_cndmask_b32_e32 v33, v33, v36, vcc
	v_mul_f32_e32 v0, v0, v33
	v_cvt_pk_bf16_f32 v0, v0, s0
	ds_write_b16 v154, v0
	v_mul_f32_e32 v0, v4, v33
	v_cvt_pk_bf16_f32 v0, v0, s0
	ds_write_b16 v154, v0 offset:32
	v_mul_f32_e32 v0, v8, v33
	v_cvt_pk_bf16_f32 v0, v0, s0
	ds_write_b16 v154, v0 offset:64
	v_mul_f32_e32 v0, v12, v33
	v_cvt_pk_bf16_f32 v0, v0, s0
	ds_write_b16 v154, v0 offset:96
	v_mul_f32_e32 v0, v16, v33
	v_cvt_pk_bf16_f32 v0, v0, s0
	ds_write_b16 v154, v0 offset:128
	v_mul_f32_e32 v0, v20, v33
	v_cvt_pk_bf16_f32 v0, v0, s0
	ds_write_b16 v154, v0 offset:160
	v_mul_f32_e32 v0, v24, v33
	v_cvt_pk_bf16_f32 v0, v0, s0
	ds_write_b16 v154, v0 offset:192
	v_mul_f32_e32 v0, 0x4b800000, v32
	v_cmp_gt_f32_e32 vcc, s2, v32
	v_mul_f32_e32 v4, v28, v33
	v_cvt_pk_bf16_f32 v4, v4, s0
	v_cndmask_b32_e32 v0, v32, v0, vcc
	v_rsq_f32_e32 v0, v0
	ds_write_b16 v154, v4 offset:224
	v_mov_b32_e32 v36, v11
	v_pk_mul_f32 v[36:37], v[36:37], v[36:37]
	v_mul_f32_e32 v4, 0x45800000, v0
	v_cndmask_b32_e32 v12, v0, v4, vcc
	v_mul_f32_e32 v0, v1, v12
	v_cvt_pk_bf16_f32 v0, v0, s0
	ds_write_b16 v154, v0 offset:272
	v_mul_f32_e32 v0, v5, v12
	v_cvt_pk_bf16_f32 v8, v0, s0
	v_mov_b32_e32 v0, v10
	v_mov_b32_e32 v1, v14
	v_pk_mul_f32 v[0:1], v[0:1], v[0:1]
	v_pk_fma_f32 v[34:35], v[2:3], v[2:3], v[34:35]
	v_mov_b32_e32 v4, v18
	v_mov_b32_e32 v5, v22
	v_mov_b32_e32 v44, v36
	v_mov_b32_e32 v45, v0
	v_pk_mul_f32 v[4:5], v[4:5], v[4:5]
	v_pk_add_f32 v[34:35], v[34:35], v[44:45] op_sel:[1,0] op_sel_hi:[0,1]
	v_mov_b32_e32 v0, v37
	v_mov_b32_e32 v32, v26
	v_mov_b32_e32 v33, v30
	v_pk_add_f32 v[0:1], v[34:35], v[0:1]
	v_mov_b32_e32 v34, v38
	v_mov_b32_e32 v35, v4
	v_pk_mul_f32 v[32:33], v[32:33], v[32:33]
	v_pk_add_f32 v[0:1], v[0:1], v[34:35]
	v_mov_b32_e32 v4, v39
	v_pk_add_f32 v[0:1], v[0:1], v[4:5]
	v_mov_b32_e32 v4, v42
	v_mov_b32_e32 v5, v32
	v_pk_add_f32 v[0:1], v[0:1], v[4:5]
	v_mov_b32_e32 v32, v43
	v_pk_add_f32 v[0:1], v[0:1], v[32:33]
	ds_bpermute_b32 v5, v142, v1
	ds_bpermute_b32 v4, v142, v0
	ds_write_b16 v154, v8 offset:304
	v_mul_f32_e32 v8, v9, v12
	v_cvt_pk_bf16_f32 v8, v8, s0
	ds_write_b16 v154, v8 offset:336
	s_waitcnt lgkmcnt(2)
	v_pk_add_f32 v[0:1], v[0:1], v[4:5]
	ds_bpermute_b32 v5, v143, v1
	ds_bpermute_b32 v4, v143, v0
	v_mul_f32_e32 v8, v13, v12
	v_cvt_pk_bf16_f32 v8, v8, s0
	ds_write_b16 v154, v8 offset:368
	v_mul_f32_e32 v8, v17, v12
	s_waitcnt lgkmcnt(1)
	v_pk_add_f32 v[0:1], v[0:1], v[4:5]
	ds_bpermute_b32 v5, v144, v1
	ds_bpermute_b32 v4, v144, v0
	v_cvt_pk_bf16_f32 v8, v8, s0
	ds_write_b16 v154, v8 offset:400
	v_mul_f32_e32 v8, v21, v12
	v_cvt_pk_bf16_f32 v13, v8, s0
	s_waitcnt lgkmcnt(1)
	v_pk_add_f32 v[4:5], v[0:1], v[4:5]
	v_lshl_add_u64 v[0:1], v[86:87], 0, s[90:91]
	global_load_dwordx4 v[32:35], v[0:1], off offset:16
	global_load_dwordx4 v[36:39], v[0:1], off
	ds_bpermute_b32 v9, v145, v5
	ds_bpermute_b32 v8, v145, v4
	ds_write_b16 v154, v13 offset:432
	v_mul_f32_e32 v13, v25, v12
	v_cvt_pk_bf16_f32 v13, v13, s0
	ds_write_b16 v154, v13 offset:464
	s_waitcnt lgkmcnt(2)
	v_pk_add_f32 v[4:5], v[4:5], v[8:9]
	s_waitcnt vmcnt(5)
	v_and_b32_e32 v13, 0xffff0000, v78
	v_pk_fma_f32 v[4:5], v[4:5], s[20:21], v[40:41] op_sel_hi:[1,0,0]
	s_waitcnt vmcnt(4)
	v_lshlrev_b32_e32 v16, 16, v74
	v_mul_f32_e32 v8, 0x4b800000, v5
	v_cmp_gt_f32_e32 vcc, s2, v5
	v_and_b32_e32 v17, 0xffff0000, v74
	s_waitcnt vmcnt(3)
	v_lshlrev_b32_e32 v20, 16, v70
	v_cndmask_b32_e32 v5, v5, v8, vcc
	v_rsq_f32_e32 v5, v5
	v_mul_f32_e32 v8, v29, v12
	v_cvt_pk_bf16_f32 v8, v8, s0
	ds_write_b16 v154, v8 offset:496
	v_mul_f32_e32 v8, 0x45800000, v5
	v_cndmask_b32_e32 v5, v5, v8, vcc
	v_mul_f32_e32 v2, v2, v5
	v_cvt_pk_bf16_f32 v2, v2, s0
	ds_write_b16 v154, v2 offset:544
	v_mul_f32_e32 v2, v6, v5
	v_cvt_pk_bf16_f32 v2, v2, s0
	ds_write_b16 v154, v2 offset:576
	v_mul_f32_e32 v2, v10, v5
	v_cvt_pk_bf16_f32 v2, v2, s0
	ds_write_b16 v154, v2 offset:608
	v_mul_f32_e32 v2, v14, v5
	v_cvt_pk_bf16_f32 v2, v2, s0
	ds_write_b16 v154, v2 offset:640
	v_mul_f32_e32 v2, v18, v5
	v_cvt_pk_bf16_f32 v2, v2, s0
	ds_write_b16 v154, v2 offset:672
	v_mul_f32_e32 v2, v22, v5
	v_cvt_pk_bf16_f32 v2, v2, s0
	ds_write_b16 v154, v2 offset:704
	v_mul_f32_e32 v2, v26, v5
	v_cvt_pk_bf16_f32 v2, v2, s0
	ds_write_b16 v154, v2 offset:736
	v_mul_f32_e32 v2, 0x4b800000, v4
	v_cmp_gt_f32_e32 vcc, s2, v4
	v_lshlrev_b32_e32 v12, 16, v78
	s_add_u32 s2, s66, s27
	v_cndmask_b32_e32 v2, v4, v2, vcc
	v_rsq_f32_e32 v2, v2
	v_mul_f32_e32 v4, v30, v5
	v_cvt_pk_bf16_f32 v4, v4, s0
	ds_write_b16 v154, v4 offset:768
	v_mul_f32_e32 v4, 0x45800000, v2
	v_cndmask_b32_e32 v2, v2, v4, vcc
	v_mul_f32_e32 v3, v3, v2
	v_cvt_pk_bf16_f32 v3, v3, s0
	ds_write_b16 v154, v3 offset:816
	v_mul_f32_e32 v3, v7, v2
	v_cvt_pk_bf16_f32 v3, v3, s0
	ds_write_b16 v154, v3 offset:848
	v_mul_f32_e32 v3, v11, v2
	v_cvt_pk_bf16_f32 v3, v3, s0
	ds_write_b16 v154, v3 offset:880
	v_mul_f32_e32 v3, v15, v2
	v_cvt_pk_bf16_f32 v3, v3, s0
	ds_write_b16 v154, v3 offset:912
	v_mul_f32_e32 v3, v19, v2
	v_cvt_pk_bf16_f32 v3, v3, s0
	ds_write_b16 v154, v3 offset:944
	v_mul_f32_e32 v3, v23, v2
	v_cvt_pk_bf16_f32 v3, v3, s0
	ds_write_b16 v154, v3 offset:976
	v_mul_f32_e32 v3, v27, v2
	v_mul_f32_e32 v2, v31, v2
	v_cvt_pk_bf16_f32 v3, v3, s0
	v_cvt_pk_bf16_f32 v2, v2, s0
	ds_write_b16 v154, v3 offset:1008
	ds_write_b16 v154, v2 offset:1040
	ds_read_b128 v[4:7], v155
	ds_read_b128 v[8:11], v156
	s_addc_u32 s3, s67, s3
	s_lshl_b32 s90, s96, 1
	v_lshl_add_u64 v[2:3], v[88:89], 0, s[90:91]
	s_waitcnt lgkmcnt(1)
; #define LAS __attribute__((address_space(3)))
; __device__ __forceinline__ unsigned pk2(float lo, float hi) { const f32x2_t v = {lo, hi}; return __builtin_bit_cast(unsigned, __builtin_convertvector(v, bf16x2_t)); }
; __device__ __forceinline__ void hgrn_pass2(const bf16* PROJ, const bf16* ST, const float* lbl, const float* gain, int e, bf16* MIX, int L, LAS unsigned char* lds) {
;     ...
; #pragma unroll
;         for (int m = 0; m < 4; ++m) { const int cc = lane + 64 * m, tl = cc >> 4, c8 = cc & 15;
;             const v4u ow = *(const LAS v4u*)(BQ + (16 * I + tl) * LSTR + c8 * 16);
;             const f32x4 ga = *(const f32x4*)(gain + 128 * h + 8 * c8), gb = *(const f32x4*)(gain + 128 * h + 8 * c8 + 4);
;             v4u yw;
; #pragma unroll
;             for (int x = 0; x < 4; ++x) { const float g0 = bflo(gch[m][x]), g1 = bfhi(gch[m][x]);
;                 const float y0 = bflo(ow[x]) * (x < 2 ? ga[2 * x] : gb[2 * x - 4]) * g0;
;                 const float y1 = bfhi(ow[x]) * (x < 2 ? ga[2 * x + 1] : gb[2 * x - 3]) * g1;
;                 yw[x] = pk2(y0, y1); }
;             *(v4u*)(MIX + (rowseg + 16 * I + tl) * D + 128 * h + 8 * c8) = yw; }
	v_lshlrev_b32_e32 v14, 16, v4
	v_and_b32_e32 v15, 0xffff0000, v4
	s_waitcnt vmcnt(0)
	v_pk_mul_f32 v[14:15], v[36:37], v[14:15]
	s_waitcnt lgkmcnt(0)
	v_lshlrev_b32_e32 v18, 16, v8
	v_pk_mul_f32 v[12:13], v[14:15], v[12:13]
	v_lshlrev_b32_e32 v14, 16, v5
	v_and_b32_e32 v15, 0xffff0000, v5
	v_cvt_pk_bf16_f32 v4, v12, v13
	v_lshlrev_b32_e32 v12, 16, v79
	v_and_b32_e32 v13, 0xffff0000, v79
	v_pk_mul_f32 v[14:15], v[38:39], v[14:15]
	v_and_b32_e32 v19, 0xffff0000, v8
	v_pk_mul_f32 v[12:13], v[14:15], v[12:13]
	v_lshlrev_b32_e32 v14, 16, v6
	v_and_b32_e32 v15, 0xffff0000, v6
	v_cvt_pk_bf16_f32 v5, v12, v13
	v_lshlrev_b32_e32 v12, 16, v80
	v_and_b32_e32 v13, 0xffff0000, v80
	v_pk_mul_f32 v[14:15], v[32:33], v[14:15]
	v_lshlrev_b32_e32 v8, 16, v9
	v_pk_mul_f32 v[12:13], v[14:15], v[12:13]
	v_lshlrev_b32_e32 v14, 16, v7
	v_and_b32_e32 v15, 0xffff0000, v7
	v_cvt_pk_bf16_f32 v6, v12, v13
	v_lshlrev_b32_e32 v12, 16, v81
	v_and_b32_e32 v13, 0xffff0000, v81
	v_pk_mul_f32 v[14:15], v[34:35], v[14:15]
	v_and_b32_e32 v9, 0xffff0000, v9
	v_pk_mul_f32 v[12:13], v[14:15], v[12:13]
	v_and_b32_e32 v21, 0xffff0000, v70
	v_cvt_pk_bf16_f32 v7, v12, v13
	v_mov_b32_e32 v13, s3
	v_or_b32_e32 v12, s2, v90
	v_lshlrev_b64 v[12:13], 11, v[12:13]
	v_lshl_add_u64 v[12:13], v[2:3], 0, v[12:13]
	global_store_dwordx4 v[12:13], v[4:7], off
	s_nop 1
	v_mov_b32_e32 v4, v36
	v_mov_b32_e32 v5, v37
	v_mov_b32_e32 v6, v38
	v_mov_b32_e32 v7, v39
	v_mov_b32_e32 v12, v32
	v_mov_b32_e32 v13, v33
	v_mov_b32_e32 v14, v34
	v_mov_b32_e32 v15, v35
	v_pk_mul_f32 v[4:5], v[4:5], v[18:19]
	s_nop 0
	v_pk_mul_f32 v[4:5], v[4:5], v[16:17]
	v_lshlrev_b32_e32 v16, 16, v75
	v_and_b32_e32 v17, 0xffff0000, v75
	v_pk_mul_f32 v[6:7], v[6:7], v[8:9]
	v_lshlrev_b32_e32 v8, 16, v10
	v_pk_mul_f32 v[6:7], v[6:7], v[16:17]
	v_and_b32_e32 v9, 0xffff0000, v10
	v_cvt_pk_bf16_f32 v4, v4, v5
	v_cvt_pk_bf16_f32 v5, v6, v7
	v_lshlrev_b32_e32 v6, 16, v76
	v_and_b32_e32 v7, 0xffff0000, v76
	v_pk_mul_f32 v[8:9], v[12:13], v[8:9]
	v_lshlrev_b32_e32 v10, 16, v11
	v_and_b32_e32 v11, 0xffff0000, v11
	v_pk_mul_f32 v[6:7], v[8:9], v[6:7]
	v_lshlrev_b32_e32 v8, 16, v77
	v_and_b32_e32 v9, 0xffff0000, v77
	v_pk_mul_f32 v[10:11], v[14:15], v[10:11]
	v_cvt_pk_bf16_f32 v6, v6, v7
	v_pk_mul_f32 v[8:9], v[10:11], v[8:9]
	s_nop 0
	v_cvt_pk_bf16_f32 v7, v8, v9
	v_mov_b32_e32 v9, s3
	v_or_b32_e32 v8, s2, v110
	v_lshlrev_b64 v[8:9], 11, v[8:9]
	v_lshl_add_u64 v[8:9], v[2:3], 0, v[8:9]
	global_store_dwordx4 v[8:9], v[4:7], off
	s_nop 1
	v_mov_b32_e32 v4, v36
	v_mov_b32_e32 v5, v37
	v_mov_b32_e32 v6, v38
	v_mov_b32_e32 v7, v39
	v_mov_b32_e32 v8, v32
	v_mov_b32_e32 v9, v33
	v_mov_b32_e32 v10, v34
	v_mov_b32_e32 v11, v35
	ds_read_b128 v[12:15], v157
	ds_read_b128 v[16:19], v158
	s_waitcnt lgkmcnt(1)
	v_lshlrev_b32_e32 v22, 16, v12
	v_and_b32_e32 v23, 0xffff0000, v12
	v_lshlrev_b32_e32 v12, 16, v13
	v_and_b32_e32 v13, 0xffff0000, v13
	v_pk_mul_f32 v[4:5], v[4:5], v[22:23]
	s_nop 0
	v_pk_mul_f32 v[4:5], v[4:5], v[20:21]
	v_lshlrev_b32_e32 v20, 16, v71
	v_and_b32_e32 v21, 0xffff0000, v71
	v_pk_mul_f32 v[6:7], v[6:7], v[12:13]
	v_lshlrev_b32_e32 v12, 16, v14
	v_pk_mul_f32 v[6:7], v[6:7], v[20:21]
	v_and_b32_e32 v13, 0xffff0000, v14
	v_cvt_pk_bf16_f32 v4, v4, v5
	v_cvt_pk_bf16_f32 v5, v6, v7
	v_lshlrev_b32_e32 v6, 16, v72
	v_and_b32_e32 v7, 0xffff0000, v72
	v_pk_mul_f32 v[8:9], v[8:9], v[12:13]
	v_lshlrev_b32_e32 v12, 16, v15
	v_and_b32_e32 v13, 0xffff0000, v15
	v_pk_mul_f32 v[6:7], v[8:9], v[6:7]
	v_lshlrev_b32_e32 v8, 16, v73
	v_and_b32_e32 v9, 0xffff0000, v73
	v_pk_mul_f32 v[10:11], v[10:11], v[12:13]
	v_cvt_pk_bf16_f32 v6, v6, v7
	v_pk_mul_f32 v[8:9], v[10:11], v[8:9]
	s_waitcnt lgkmcnt(0)
	v_lshlrev_b32_e32 v12, 16, v16
	v_cvt_pk_bf16_f32 v7, v8, v9
	v_mov_b32_e32 v9, s3
	v_or_b32_e32 v8, s2, v114
	v_lshlrev_b64 v[8:9], 11, v[8:9]
	v_lshl_add_u64 v[8:9], v[2:3], 0, v[8:9]
	global_store_dwordx4 v[8:9], v[4:7], off
	s_nop 1
	v_mov_b32_e32 v4, v36
	v_mov_b32_e32 v5, v37
	v_mov_b32_e32 v6, v38
	v_mov_b32_e32 v7, v39
	v_mov_b32_e32 v8, v32
	v_mov_b32_e32 v9, v33
	v_mov_b32_e32 v10, v34
	v_mov_b32_e32 v11, v35
	v_and_b32_e32 v13, 0xffff0000, v16
	v_lshlrev_b32_e32 v0, 16, v66
	v_and_b32_e32 v1, 0xffff0000, v66
	v_pk_mul_f32 v[4:5], v[4:5], v[12:13]
	s_nop 0
	v_pk_mul_f32 v[0:1], v[4:5], v[0:1]
	v_lshlrev_b32_e32 v12, 16, v17
	v_and_b32_e32 v13, 0xffff0000, v17
	v_cvt_pk_bf16_f32 v4, v0, v1
	v_lshlrev_b32_e32 v0, 16, v67
	v_and_b32_e32 v1, 0xffff0000, v67
	v_pk_mul_f32 v[6:7], v[6:7], v[12:13]
	s_nop 0
	v_pk_mul_f32 v[0:1], v[6:7], v[0:1]
	v_lshlrev_b32_e32 v6, 16, v18
	v_and_b32_e32 v7, 0xffff0000, v18
	v_cvt_pk_bf16_f32 v5, v0, v1
	v_lshlrev_b32_e32 v0, 16, v68
	v_and_b32_e32 v1, 0xffff0000, v68
	v_pk_mul_f32 v[6:7], v[8:9], v[6:7]
	v_lshlrev_b32_e32 v8, 16, v19
	v_pk_mul_f32 v[0:1], v[6:7], v[0:1]
	v_and_b32_e32 v9, 0xffff0000, v19
	v_cvt_pk_bf16_f32 v6, v0, v1
	v_lshlrev_b32_e32 v0, 16, v69
	v_and_b32_e32 v1, 0xffff0000, v69
	v_pk_mul_f32 v[8:9], v[10:11], v[8:9]
	s_nop 0
	v_pk_mul_f32 v[0:1], v[8:9], v[0:1]
	s_nop 0
	v_cvt_pk_bf16_f32 v7, v0, v1
	v_mov_b32_e32 v1, s3
	v_or_b32_e32 v0, s2, v118
	v_readlane_b32 s2, v247, 18
	v_lshlrev_b64 v[0:1], 11, v[0:1]
	s_add_i32 s26, s26, s2
	v_readlane_b32 s2, v247, 61
	v_lshl_add_u64 v[0:1], v[2:3], 0, v[0:1]
	s_cmp_ge_i32 s26, s2
	v_readlane_b32 s3, v247, 19
	global_store_dwordx4 v[0:1], v[4:7], off
	s_cbranch_scc1 .LBB0_266

; #define LAS __attribute__((address_space(3)))
; __device__ __forceinline__ void hgrn_pass2(const bf16* PROJ, const bf16* ST, const float* lbl, const float* gain, int e, bf16* MIX, int L, LAS unsigned char* lds) {
;     ...
;         for (int dir = 0; dir < 2; ++dir) {
;             v4u sreg[4];
;             {   v4u cz[4], cq[4];
;                 hgrn_ld_chunks(pb + 512 + 512 * dir, tid, cz); hgrn_ld_chunks(pb, tid, cq);
;                 const bf16* Sg = ST + (size_t)(u * 2 + dir) * 16384;
; #pragma unroll
;                 for (int m = 0; m < 4; ++m) sreg[m] = *(const v4u*)(Sg + (size_t)(tid + 512 * m) * 8);
;                 hgrn_st_chunks(BK, tid, cz); hgrn_st_chunks(BQ, tid, cq); }
;             __syncthreads();
; #pragma unroll
;             for (int m = 0; m < 4; ++m) { const int c = tid + 512 * m; *(LAS v4u*)(SI + (c >> 4) * LSTR + (c & 15) * 16) = sreg[m]; }
;     ...
;         { v4u cv[4]; hgrn_ld_chunks(pb + 1536, tid, cv); hgrn_st_chunks(SI, tid, cv); }
.LBB0_274:
	s_lshl_b32 s90, s20, 10
	s_or_b32 s20, s20, s39
	s_ashr_i32 s21, s20, 31
	s_xor_b64 s[34:35], s[2:3], -1
	s_lshl_b64 s[20:21], s[20:21], 15
	v_lshl_add_u64 v[78:79], v[130:131], 0, s[90:91]
	s_add_u32 s20, s33, s20
	v_lshl_add_u64 v[66:67], v[78:79], 0, v[92:93]
	s_addc_u32 s21, s92, s21
	global_load_dwordx4 v[66:69], v[66:67], off offset:1024
	v_lshl_add_u64 v[70:71], v[78:79], 0, v[94:95]
	v_lshl_add_u64 v[74:75], v[78:79], 0, v[96:97]
	v_lshl_add_u64 v[78:79], v[78:79], 0, v[98:99]
	v_lshl_add_u64 v[182:183], s[20:21], 0, v[104:105]
	global_load_dwordx4 v[70:73], v[70:71], off offset:1024
	v_lshl_add_u64 v[174:175], s[20:21], 0, v[100:101]
	global_load_dwordx4 v[74:77], v[74:75], off offset:1024
	s_nop 0
	global_load_dwordx4 v[78:81], v[78:79], off offset:1024
	s_nop 0
	global_load_dwordx4 v[82:85], v[122:123], off
	global_load_dwordx4 v[162:165], v[124:125], off
	global_load_dwordx4 v[166:169], v[126:127], off
	global_load_dwordx4 v[170:173], v[128:129], off
	v_lshl_add_u64 v[178:179], s[20:21], 0, v[102:103]
	global_load_dwordx4 v[188:191], v[182:183], off
	v_lshl_add_u64 v[182:183], s[20:21], 0, v[106:107]
	global_load_dwordx4 v[174:177], v[174:175], off
	s_mov_b64 s[86:87], -1
	global_load_dwordx4 v[178:181], v[178:179], off
	s_mov_b32 s90, 0
	global_load_dwordx4 v[192:195], v[182:183], off
	v_add_u32_e32 v182, v115, v119
	s_waitcnt vmcnt(11)
	ds_write_b128 v182, v[66:69] offset:34816
	v_add_u32_e32 v66, v115, v132
	v_add_u32_e32 v67, v115, v133
	v_add_u32_e32 v68, v115, v134
	s_waitcnt vmcnt(10)
	ds_write_b128 v66, v[70:73] offset:34816
	s_waitcnt vmcnt(9)
	ds_write_b128 v67, v[74:77] offset:34816
	s_waitcnt vmcnt(8)
	ds_write_b128 v68, v[78:81] offset:34816
	s_waitcnt vmcnt(7)
	ds_write_b128 v182, v[82:85]
	s_waitcnt vmcnt(6)
	ds_write_b128 v66, v[162:165]
	s_waitcnt vmcnt(5)
	ds_write_b128 v67, v[166:169]
	s_waitcnt vmcnt(4)
	ds_write_b128 v68, v[170:173]
	v_add_u32_e32 v162, v135, v119
	v_add_u32_e32 v163, v135, v132
	v_add_u32_e32 v164, v135, v133
	v_add_u32_e32 v165, v135, v134
	s_waitcnt lgkmcnt(0)
	s_barrier
	s_waitcnt vmcnt(2)
	ds_write_b128 v162, v[174:177]
	s_waitcnt vmcnt(1)
	ds_write_b128 v163, v[178:181]
	ds_write_b128 v164, v[188:191]
	s_waitcnt vmcnt(0)
	ds_write_b128 v165, v[192:195]
	s_and_b64 vcc, exec, s[34:35]
	s_cbranch_vccz .Lp2_nov
	global_load_dwordx4 v[232:235], v[122:123], off offset:3072
	global_load_dwordx4 v[236:239], v[124:125], off offset:3072
	global_load_dwordx4 v[240:243], v[126:127], off offset:3072
	global_load_dwordx4 v[252:255], v[128:129], off offset:3072
.Lp2_nov:
	s_branch .LBB0_277
.LBB0_275:
	v_add_f32_e32 v181, v216, v69
	v_exp_f32_e32 v197, v181
	v_add_f32_e32 v181, v181, v71
	v_exp_f32_e32 v196, v181
	v_add_f32_e32 v181, v181, v73
	v_add_f32_e32 v202, v214, v170
	v_exp_f32_e32 v195, v181
	v_add_f32_e32 v181, v181, v75
	v_add_f32_e32 v203, v202, v168
	v_exp_f32_e32 v194, v181
	v_add_f32_e32 v181, v181, v77
	v_add_f32_e32 v204, v203, v166
	v_exp_f32_e32 v193, v181
	v_add_f32_e32 v181, v181, v79
	v_add_f32_e32 v205, v204, v84
	v_exp_f32_e32 v192, v181
	v_add_f32_e32 v181, v181, v81
	v_add_f32_e32 v206, v205, v83
	v_exp_f32_e32 v191, v181
	v_add_f32_e32 v181, v181, v83
	v_add_f32_e32 v207, v206, v81
	v_exp_f32_e32 v190, v181
	v_add_f32_e32 v181, v181, v84
	v_add_f32_e32 v208, v207, v79
	v_exp_f32_e32 v189, v181
	v_add_f32_e32 v181, v181, v166
	v_add_f32_e32 v209, v208, v77
	v_exp_f32_e32 v188, v181
	v_add_f32_e32 v181, v181, v168
	v_add_f32_e32 v210, v209, v75
	v_exp_f32_e32 v183, v181
	v_add_f32_e32 v181, v181, v170
	v_add_f32_e32 v211, v210, v73
	v_add_f32_e32 v199, v181, v172
	v_add_f32_e32 v212, v211, v71
	v_add_f32_e32 v200, v199, v213
	v_add_f32_e32 v213, v212, v69
	v_exp_f32_e32 v201, v202
	v_exp_f32_e32 v202, v203
	v_exp_f32_e32 v203, v204
	v_exp_f32_e32 v204, v205
	v_exp_f32_e32 v205, v206
	v_exp_f32_e32 v206, v207
	v_exp_f32_e32 v207, v208
	v_exp_f32_e32 v208, v209
	v_exp_f32_e32 v209, v210
	v_exp_f32_e32 v210, v211
	v_exp_f32_e32 v211, v212
	v_exp_f32_e32 v212, v213
	v_add_f32_e32 v213, v213, v67
	v_exp_f32_e32 v213, v213
	v_exp_f32_e32 v198, v216
	v_exp_f32_e32 v182, v181
	v_exp_f32_e32 v181, v199
	v_exp_f32_e32 v199, v200
	ds_write_b32 v215, v200 offset:512
	v_exp_f32_e32 v200, v214
	v_mul_f32_e32 v175, v175, v213

; #define LAS __attribute__((address_space(3)))
; __global__ void __launch_bounds__(NTHR, 2) fwd_kernel(Params p) {
;     extern __shared__ __attribute__((aligned(16))) unsigned char lds_raw[];
;     LAS unsigned char* lds = (LAS unsigned char*)lds_raw;
;     cg::grid_group grid = cg::this_grid();
;     volatile LAS unsigned* bst = (volatile LAS unsigned*)(lds + LDS_BYTES - 64);
;     if (threadIdx.x < 2) bst[threadIdx.x] = 0u;
;     __syncthreads();
;     XcdBarrier bar = xcd_barrier_post((unsigned*)p.ws, bst);
;     for (int ph = p.ph_lo; ph < p.ph_hi; ++ph) {
;         int tid_ = threadIdx.x; asm volatile("" : "+v"(tid_)); const int tid = tid_, lane = tid & 63, wave = __builtin_amdgcn_readfirstlane(tid >> 6);
	.amdhsa_kernel _Z10fwd_kernel6Params
		.amdhsa_group_segment_fixed_size 0
		.amdhsa_private_segment_fixed_size 0
		.amdhsa_kernarg_size 408
		.amdhsa_user_sgpr_count 2
		.amdhsa_user_sgpr_dispatch_ptr 0
		.amdhsa_user_sgpr_queue_ptr 0
		.amdhsa_user_sgpr_kernarg_segment_ptr 1
		.amdhsa_user_sgpr_dispatch_id 0
		.amdhsa_user_sgpr_kernarg_preload_length 0
		.amdhsa_user_sgpr_kernarg_preload_offset 0
		.amdhsa_user_sgpr_private_segment_size 0
		.amdhsa_uses_dynamic_stack 0
		.amdhsa_enable_private_segment 0
		.amdhsa_system_sgpr_workgroup_id_x 1
		.amdhsa_system_sgpr_workgroup_id_y 0
		.amdhsa_system_sgpr_workgroup_id_z 0
		.amdhsa_system_sgpr_workgroup_info 0
		.amdhsa_system_vgpr_workitem_id 2
		.amdhsa_next_free_vgpr 256
		.amdhsa_next_free_sgpr 102
		.amdhsa_accum_offset 256
		.amdhsa_reserve_vcc 1
		.amdhsa_float_round_mode_32 0
		.amdhsa_float_round_mode_16_64 0
		.amdhsa_float_denorm_mode_32 3
		.amdhsa_float_denorm_mode_16_64 3
		.amdhsa_dx10_clamp 1
		.amdhsa_ieee_mode 1
		.amdhsa_fp16_overflow 0
		.amdhsa_tg_split 0
		.amdhsa_exception_fp_ieee_invalid_op 0
		.amdhsa_exception_fp_denorm_src 0
		.amdhsa_exception_fp_ieee_div_zero 0
		.amdhsa_exception_fp_ieee_overflow 0
		.amdhsa_exception_fp_ieee_underflow 0
		.amdhsa_exception_fp_ieee_inexact 0
		.amdhsa_exception_int_div_zero 0
	.end_amdhsa_kernel

; #define LAS __attribute__((address_space(3)))
; __global__ void __launch_bounds__(NTHR, 2) fwd_kernel(Params p) {
;     extern __shared__ __attribute__((aligned(16))) unsigned char lds_raw[];
;     LAS unsigned char* lds = (LAS unsigned char*)lds_raw;
;     cg::grid_group grid = cg::this_grid();
;     volatile LAS unsigned* bst = (volatile LAS unsigned*)(lds + LDS_BYTES - 64);
;     if (threadIdx.x < 2) bst[threadIdx.x] = 0u;
;     __syncthreads();
;     XcdBarrier bar = xcd_barrier_post((unsigned*)p.ws, bst);
;     for (int ph = p.ph_lo; ph < p.ph_hi; ++ph) {
;         int tid_ = threadIdx.x; asm volatile("" : "+v"(tid_)); const int tid = tid_, lane = tid & 63, wave = __builtin_amdgcn_readfirstlane(tid >> 6);
amdhsa.kernels:
  - .agpr_count:     0
    .args:
      - .offset:         0
        .size:           152
        .value_kind:     by_value
      - .offset:         152
        .size:           4
        .value_kind:     hidden_block_count_x
      - .offset:         156
        .size:           4
        .value_kind:     hidden_block_count_y
      - .offset:         160
        .size:           4
        .value_kind:     hidden_block_count_z
      - .offset:         164
        .size:           2
        .value_kind:     hidden_group_size_x
      - .offset:         166
        .size:           2
        .value_kind:     hidden_group_size_y
      - .offset:         168
        .size:           2
        .value_kind:     hidden_group_size_z
      - .offset:         170
        .size:           2
        .value_kind:     hidden_remainder_x
      - .offset:         172
        .size:           2
        .value_kind:     hidden_remainder_y
      - .offset:         174
        .size:           2
        .value_kind:     hidden_remainder_z
      - .offset:         192
        .size:           8
        .value_kind:     hidden_global_offset_x
      - .offset:         200
        .size:           8
        .value_kind:     hidden_global_offset_y
      - .offset:         208
        .size:           8
        .value_kind:     hidden_global_offset_z
      - .offset:         216
        .size:           2
        .value_kind:     hidden_grid_dims
      - .offset:         240
        .size:           8
        .value_kind:     hidden_multigrid_sync_arg
      - .offset:         272
        .size:           4
        .value_kind:     hidden_dynamic_lds_size
    .group_segment_fixed_size: 0
    .kernarg_segment_align: 8
    .kernarg_segment_size: 408
    .language:       OpenCL C
    .language_version:
      - 2
      - 0
    .max_flat_workgroup_size: 512
    .name:           _Z10fwd_kernel6Params
    .private_segment_fixed_size: 0
    .sgpr_count:     108
    .sgpr_spill_count: 208
    .symbol:         _Z10fwd_kernel6Params.kd
    .uniform_work_group_size: 1
    .uses_dynamic_stack: false
    .vgpr_count:     256
    .vgpr_spill_count: 0
    .wavefront_size: 64
